# strategy 4: one static s_setprio 1 for waves 4-7 in the chunk_pre task loop and the attention work queue, back to 0 at the end of P8 (on top of v020)
# speedup vs baseline: 1.0065x; 1.0044x over previous
; template <int LO, int HI> __global__ void __launch_bounds__(NTHR, 2) mega(P p) {
;     ...
;         if (F.bid < NSEQ_P * 32) {
;             CKIN_DECL(i); CKIN_LOAD(i, F.bid); int ptag0 = -1, ptag1 = -1;
;             __syncthreads();
;             for (int task = F.bid; task < NSEQ_P * 32; task += F.G) chunk_pre(p, F, task, task + F.G < NSEQ_P * 32 ? task + F.G : task, icr, ick, icv, ipr, ipk, ipv, ia0, ia1, iw0, iw1, ptag0, ptag1); }
.LBB0_1613:
	v_readfirstlane_b32 s6, v0
	s_nop 3
	s_bitcmp1_b32 s6, 8
	s_cbranch_scc0 .Lprio_p7_done
	s_setprio 1

; template <int LO, int HI> __global__ void __launch_bounds__(NTHR, 2) mega(P p) {
;     ...
;         { unsigned* qctr = (unsigned*)(ws + WS_CTL) + 8192;
; #pragma nounroll
;           for (;;) {
;               if (F.tid == 0) MISC[0] = __hip_atomic_fetch_add(qctr, 1u, __ATOMIC_RELAXED, __HIP_MEMORY_SCOPE_AGENT);
;               __syncthreads();
;               const int k = (int)MISC[0];
;               __syncthreads();
;               constexpr int NATT = 576, NCONV = (TR_NLATE + 15) / 16;
;               if (k >= NATT + NCONV) break;
;               int ia = -1, ic = -1;
;               if (k < 2 * NATT) { if (k & 1) ic = k >> 1; else ia = k >> 1; } else ic = k - NATT;
;               if (ic >= 0) { tr_late_batch(p, F, ic); continue; }
;               const bool is_s = ia < 64; const int kk = is_s ? ia : ia - 64;
;               attn_item(p, F, is_s, is_s ? kk >> 1 : (kk & 15) >> 1, kk & 1, is_s ? 0 : 31 - (kk >> 4)); } }
.LBB0_1864:
	v_readfirstlane_b32 s0, v0
	s_nop 3
	s_bitcmp1_b32 s0, 8
	s_cbranch_scc0 .Lprio_p8_done
	s_setprio 1

; __device__ __forceinline__ unsigned xb_ld(unsigned* p)              { return __hip_atomic_load(p, __ATOMIC_RELAXED, __HIP_MEMORY_SCOPE_AGENT); }
; __device__ __forceinline__ unsigned xb_add(unsigned* p, unsigned v) { return __hip_atomic_fetch_add(p, v, __ATOMIC_RELAXED, __HIP_MEMORY_SCOPE_AGENT); }
; __device__ __forceinline__ void xcd_barrier_complete(unsigned* bar, unsigned x, unsigned& nloc, unsigned& nx) {
;     const unsigned G = gridDim.x * gridDim.y * gridDim.z;
;     unsigned sum, cnt, mine, sp = 0u;
;     for (;;) {
;         sum = 0u; cnt = 0u; mine = 0u;
; #pragma unroll
;         for (unsigned j = 0; j < 16; ++j) { const unsigned c = xb_ld(&bar[XB_XCNT(j)]); sum += c; cnt += (c > 0u) ? 1u : 0u; mine = (j == x) ? c : mine; }
; __device__ __forceinline__ void xcd_barrier(const XcdBarrier& b) {
;     asm volatile("s_waitcnt vmcnt(0)" ::: "memory");
;     __syncthreads();
;     if (threadIdx.x == 0) {
;         unsigned* bar = b.bar;
;         __builtin_amdgcn_s_waitcnt(0);
;         unsigned nloc = b.st[0], nx = b.st[1];
;         if (nloc == 0u) { xcd_barrier_complete(bar, b.x, nloc, nx); b.st[0] = nloc; b.st[1] = nx; }
;         const unsigned old = xb_add(&bar[XB_XSUB(b.x)], 1u);
.LBB0_2400:
	s_setprio 0
	s_waitcnt vmcnt(0)
	s_barrier
	s_mov_b64 s[0:1], exec
	v_readlane_b32 s2, v253, 25
	v_readlane_b32 s50, v253, 28
	v_readlane_b32 s3, v253, 26
	v_readlane_b32 s68, v253, 4
	v_readlane_b32 s70, v254, 29
	v_readlane_b32 s72, v254, 8
	v_readlane_b32 s51, v253, 29
	v_readlane_b32 s56, v254, 25
	v_readlane_b32 s82, v252, 5
	v_readlane_b32 s58, v254, 23
	v_readlane_b32 s60, v252, 23
	v_readlane_b32 s64, v252, 17
	s_and_b64 s[2:3], s[0:1], s[2:3]
	v_readlane_b32 s69, v253, 5
	v_readlane_b32 s71, v254, 30
	v_readlane_b32 s73, v254, 9
	v_readlane_b32 s74, v254, 16
	v_readlane_b32 s57, v254, 26
	v_readlane_b32 s75, v252, 10
	v_readlane_b32 s80, v252, 9
	v_readlane_b32 s83, v252, 6
	v_readlane_b32 s59, v254, 24
	v_readlane_b32 s61, v252, 24
	v_readlane_b32 s51, v252, 36
	v_readlane_b32 s62, v252, 37
	v_readlane_b32 s63, v252, 35
	v_readlane_b32 s65, v252, 18
	s_mov_b64 exec, s[2:3]
	s_cbranch_execz .LBB0_2452
	s_add_i32 s2, 0, 0x23f20
	v_mov_b32_e32 v1, s2
	s_waitcnt vmcnt(0) expcnt(0) lgkmcnt(0)
	ds_read_b32 v3, v1
	s_add_i32 s2, 0, 0x23f24
	v_mov_b32_e32 v1, s2
	ds_read_b32 v1, v1
	s_waitcnt lgkmcnt(1)
	v_cmp_ne_u32_e32 vcc, 0, v3
	s_cbranch_vccnz .LBB0_2416
	v_readlane_b32 s4, v253, 2
	v_readlane_b32 s5, v253, 3
	s_load_dwordx2 s[2:3], s[4:5], 0x4
	v_readlane_b32 s4, v253, 32
	v_readlane_b32 s18, v253, 46
	v_readlane_b32 s19, v253, 47
	v_readlane_b32 s6, v253, 34
	v_readlane_b32 s16, v253, 44
	v_readlane_b32 s17, v253, 45
	s_mov_b64 s[54:55], s[18:19]
	v_readlane_b32 s7, v253, 35
	s_add_u32 s6, s54, 0x4200
	v_readlane_b32 s8, v253, 36
	s_addc_u32 s7, s55, 0
	v_readlane_b32 s9, v253, 37
	s_add_u32 s8, s54, 0x4400
	v_readlane_b32 s10, v253, 38
	s_addc_u32 s9, s55, 0
	v_readlane_b32 s11, v253, 39
	s_add_u32 s10, s54, 0x4500
	v_readlane_b32 s12, v253, 40
	s_addc_u32 s11, s55, 0
	v_readlane_b32 s13, v253, 41
	s_add_u32 s12, s54, 0x4600
	v_readlane_b32 s14, v253, 42
	s_addc_u32 s13, s55, 0
	v_readlane_b32 s15, v253, 43
	s_add_u32 s14, s54, 0x4700
	s_addc_u32 s15, s55, 0
	s_mov_b64 s[52:53], s[16:17]
	s_add_u32 s16, s54, 0x4800
	s_addc_u32 s17, s55, 0
	s_add_u32 s18, s54, 0x4900
	s_addc_u32 s19, s55, 0
	s_add_u32 s20, s54, 0x4a00
	s_addc_u32 s21, s55, 0
	s_add_u32 s22, s54, 0x4b00
	s_addc_u32 s23, s55, 0
	s_add_u32 s24, s54, 0x4c00
	s_addc_u32 s25, s55, 0
	s_add_u32 s26, s54, 0x4d00
	s_addc_u32 s27, s55, 0
	s_add_u32 s28, s54, 0x4e00
	s_addc_u32 s29, s55, 0
	s_add_u32 s30, s54, 0x4f00
	s_addc_u32 s31, s55, 0
	s_add_u32 s34, s54, 0x5000
	s_addc_u32 s35, s55, 0
	s_add_u32 s36, s54, 0x5100
	s_addc_u32 s37, s55, 0
	v_readlane_b32 s5, v253, 33
	s_add_u32 s38, s54, 0x5200
	v_readlane_b32 s4, v253, 0
	s_addc_u32 s39, s55, 0
	s_waitcnt lgkmcnt(0)
	s_mul_i32 s2, s2, s4
	s_add_u32 s40, s54, 0x5300
	s_mul_i32 s2, s2, s3
	s_addc_u32 s41, s55, 0
	s_mov_b32 s3, 1
	v_mov_b32_e32 v17, 0
	v_readlane_b32 s5, v253, 1
	s_branch .LBB0_2404
